# grid barrier: XCD leaders poll the cross-XCC generation word without the sleep between polls
# speedup vs baseline: 1.0039x; 1.0027x over previous
.LBB0_1517:
	global_load_dword v0, v153, s[76:77] sc1
	s_waitcnt vmcnt(0)
	v_cmp_ne_u32_e32 vcc, v0, v1
	s_or_b64 s[14:15], vcc, s[14:15]
	s_andn2_b64 exec, exec, s[14:15]
	s_cbranch_execnz .LBB0_1517
